# v079 + tile-boundary barrier re-pairing in the GU GEMM: waves 0-3 release the lagging half right after the K-loop so both halves run their epilogues concurrently; waves 4-7 take the matching extra bar
# speedup vs baseline: 1.0233x; 1.0111x over previous
.LBB0_1435:
	s_ashr_i32 s17, s16, 31
	v_cmp_lt_i64_e32 vcc, s[18:19], v[186:187]
	s_lshl_b64 s[18:19], s[16:17], 19
	s_add_u32 s18, s47, s18
	s_addc_u32 s19, s54, s19
	s_and_b64 s[20:21], vcc, exec
	s_cselect_b32 s17, s19, s7
	s_cselect_b32 s66, s18, s6
	s_ashr_i32 s13, s12, 31
	s_lshl_b64 s[20:21], s[12:13], 19
	s_add_u32 s20, s37, s20
	s_addc_u32 s21, s46, s21
	s_and_b64 s[52:53], vcc, exec
	s_cselect_b32 s13, s21, s51
	s_cselect_b32 s67, s20, s50
	s_add_u32 s6, s6, 0x40080
	s_addc_u32 s7, s7, 0
	s_add_u32 s68, s50, 0x100
	v_mov_b64_e32 v[0:1], 0
	v_mov_b64_e32 v[2:3], 0
	v_mov_b64_e32 v[4:5], 0
	s_addc_u32 s69, s51, 0
	s_mov_b32 s70, -2
	v_add_u32_e32 v174, 0x10000, v200
	s_cmpk_gt_u32 s24, 0xff
	s_cbranch_scc0 .Ltb_e2_skip
	s_cmp_gt_u32 s65, 1
	s_cbranch_scc0 .Ltb_e2_skip
	s_barrier
.Ltb_e2_skip:
	.p2alignl 6, 3212836864
.LBB0_1436:
	s_add_u32 s28, s6, 0xfffc0080
	s_addc_u32 s29, s7, -1
	s_add_i32 s71, 0, 0x10000
	ds_read_b128 v[128:131], v174
	ds_read_b128 v[132:135], v174 offset:1024
	ds_read_b128 v[136:139], v174 offset:2048
	ds_read_b128 v[140:143], v174 offset:3072
	s_cmp_eq_u32 s70, 12
	s_cselect_b32 s53, s17, s29
	s_cselect_b32 s52, s66, s28
	s_cselect_b32 s51, s13, s69
	s_cselect_b32 s50, s67, s68
	s_add_i32 m0, s56, 0xc000
	ds_read_b128 v[144:147], v201
	ds_read_b128 v[152:155], v201 offset:2048
	ds_read_b128 v[170:173], v201 offset:4096
	ds_read_b128 v[192:195], v201 offset:6144
	ds_read_b128 v[148:151], v201 offset:1024
	ds_read_b128 v[166:169], v201 offset:3072
	ds_read_b128 v[188:191], v201 offset:5120
	ds_read_b128 v[202:205], v201 offset:7168
	global_load_lds_dwordx4 v162, s[6:7]
	s_add_i32 m0, s56, 0xe000
	s_nop 0
	global_load_lds_dwordx4 v164, s[6:7]
	s_waitcnt lgkmcnt(8)
	s_barrier
	s_waitcnt lgkmcnt(7)
	v_mfma_f32_16x16x32_bf16 v[124:127], v[128:131], v[144:147], v[124:127]
	v_mfma_f32_16x16x32_bf16 v[116:119], v[136:139], v[144:147], v[116:119]
	s_waitcnt lgkmcnt(6)
	v_mfma_f32_16x16x32_bf16 v[108:111], v[128:131], v[152:155], v[108:111]
	v_mfma_f32_16x16x32_bf16 v[100:103], v[136:139], v[152:155], v[100:103]
	s_waitcnt lgkmcnt(5)
	v_mfma_f32_16x16x32_bf16 v[92:95], v[128:131], v[170:173], v[92:95]
	v_mfma_f32_16x16x32_bf16 v[84:87], v[136:139], v[170:173], v[84:87]
	s_waitcnt lgkmcnt(4)
	v_mfma_f32_16x16x32_bf16 v[76:79], v[128:131], v[192:195], v[76:79]
	v_mfma_f32_16x16x32_bf16 v[68:71], v[136:139], v[192:195], v[68:71]
	s_waitcnt lgkmcnt(3)
	v_mfma_f32_16x16x32_bf16 v[124:127], v[132:135], v[148:151], v[124:127]
	v_mfma_f32_16x16x32_bf16 v[116:119], v[140:143], v[148:151], v[116:119]
	s_waitcnt lgkmcnt(2)
	v_mfma_f32_16x16x32_bf16 v[108:111], v[132:135], v[166:169], v[108:111]
	v_mfma_f32_16x16x32_bf16 v[100:103], v[140:143], v[166:169], v[100:103]
	s_waitcnt lgkmcnt(1)
	v_mfma_f32_16x16x32_bf16 v[92:95], v[132:135], v[188:191], v[92:95]
	v_mfma_f32_16x16x32_bf16 v[84:87], v[140:143], v[188:191], v[84:87]
	s_waitcnt lgkmcnt(0)
	v_mfma_f32_16x16x32_bf16 v[76:79], v[132:135], v[202:205], v[76:79]
	v_mfma_f32_16x16x32_bf16 v[68:71], v[140:143], v[202:205], v[68:71]
	s_barrier
	s_add_i32 s28, 0, 0x14000
	s_add_i32 s29, s71, s55
	ds_read_b128 v[206:209], v174 offset:16384
	ds_read_b128 v[210:213], v174 offset:17408
	ds_read_b128 v[214:217], v174 offset:18432
	ds_read_b128 v[232:235], v174 offset:19456
	s_mov_b32 m0, s29
	s_nop 0
	global_load_lds_dwordx4 v176, s[50:51]
	s_add_i32 m0, s29, 0x2000
	s_nop 0
	global_load_lds_dwordx4 v160, s[50:51]
	s_barrier
	s_waitcnt lgkmcnt(3)
	v_mfma_f32_16x16x32_bf16 v[120:123], v[206:209], v[144:147], v[120:123]
	s_waitcnt lgkmcnt(1)
	v_mfma_f32_16x16x32_bf16 v[112:115], v[214:217], v[144:147], v[112:115]
	v_mfma_f32_16x16x32_bf16 v[104:107], v[206:209], v[152:155], v[104:107]
	v_mfma_f32_16x16x32_bf16 v[96:99], v[214:217], v[152:155], v[96:99]
	v_mfma_f32_16x16x32_bf16 v[88:91], v[206:209], v[170:173], v[88:91]
	v_mfma_f32_16x16x32_bf16 v[80:83], v[214:217], v[170:173], v[80:83]
	v_mfma_f32_16x16x32_bf16 v[72:75], v[206:209], v[192:195], v[72:75]
	v_mfma_f32_16x16x32_bf16 v[64:67], v[214:217], v[192:195], v[64:67]
	v_mfma_f32_16x16x32_bf16 v[120:123], v[210:213], v[148:151], v[120:123]
	s_waitcnt lgkmcnt(0)
	v_mfma_f32_16x16x32_bf16 v[112:115], v[232:235], v[148:151], v[112:115]
	v_mfma_f32_16x16x32_bf16 v[104:107], v[210:213], v[166:169], v[104:107]
	v_mfma_f32_16x16x32_bf16 v[96:99], v[232:235], v[166:169], v[96:99]
	v_mfma_f32_16x16x32_bf16 v[88:91], v[210:213], v[188:191], v[88:91]
	v_mfma_f32_16x16x32_bf16 v[80:83], v[232:235], v[188:191], v[80:83]
	v_mfma_f32_16x16x32_bf16 v[72:75], v[210:213], v[202:205], v[72:75]
	v_mfma_f32_16x16x32_bf16 v[64:67], v[232:235], v[202:205], v[64:67]
	s_mov_b32 m0, s56
	s_barrier
	ds_read_b128 v[144:147], v201 offset:16384
	ds_read_b128 v[152:155], v201 offset:18432
	ds_read_b128 v[170:173], v201 offset:20480
	ds_read_b128 v[192:195], v201 offset:22528
	ds_read_b128 v[148:151], v201 offset:17408
	ds_read_b128 v[166:169], v201 offset:19456
	ds_read_b128 v[188:191], v201 offset:21504
	ds_read_b128 v[202:205], v201 offset:23552
	global_load_lds_dwordx4 v156, s[52:53]
	s_mov_b32 m0, s57
	s_nop 0
	global_load_lds_dwordx4 v158, s[52:53]
	s_barrier
	s_waitcnt lgkmcnt(7)
	v_mfma_f32_16x16x32_bf16 v[60:63], v[128:131], v[144:147], v[60:63]
	v_mfma_f32_16x16x32_bf16 v[52:55], v[136:139], v[144:147], v[52:55]
	s_waitcnt lgkmcnt(6)
	v_mfma_f32_16x16x32_bf16 v[44:47], v[128:131], v[152:155], v[44:47]
	v_mfma_f32_16x16x32_bf16 v[36:39], v[136:139], v[152:155], v[36:39]
	s_waitcnt lgkmcnt(5)
	v_mfma_f32_16x16x32_bf16 v[28:31], v[128:131], v[170:173], v[28:31]
	v_mfma_f32_16x16x32_bf16 v[20:23], v[136:139], v[170:173], v[20:23]
	s_waitcnt lgkmcnt(4)
	v_mfma_f32_16x16x32_bf16 v[12:15], v[128:131], v[192:195], v[12:15]
	v_mfma_f32_16x16x32_bf16 v[4:7], v[136:139], v[192:195], v[4:7]
	s_waitcnt lgkmcnt(3)
	v_mfma_f32_16x16x32_bf16 v[60:63], v[132:135], v[148:151], v[60:63]
	v_mfma_f32_16x16x32_bf16 v[52:55], v[140:143], v[148:151], v[52:55]
	s_waitcnt lgkmcnt(2)
	v_mfma_f32_16x16x32_bf16 v[44:47], v[132:135], v[166:169], v[44:47]
	v_mfma_f32_16x16x32_bf16 v[36:39], v[140:143], v[166:169], v[36:39]
	s_waitcnt lgkmcnt(1)
	v_mfma_f32_16x16x32_bf16 v[28:31], v[132:135], v[188:191], v[28:31]
	v_mfma_f32_16x16x32_bf16 v[20:23], v[140:143], v[188:191], v[20:23]
	s_waitcnt lgkmcnt(0)
	v_mfma_f32_16x16x32_bf16 v[12:15], v[132:135], v[202:205], v[12:15]
	v_mfma_f32_16x16x32_bf16 v[4:7], v[140:143], v[202:205], v[4:7]
	s_barrier
	s_add_u32 s72, s50, 0x40000
	s_addc_u32 s73, s51, 0
	s_add_i32 s28, s28, s55
	s_mov_b32 m0, s28
	s_nop 0
	global_load_lds_dwordx4 v176, s[72:73]
	s_add_i32 m0, s28, 0x2000
	s_nop 0
	global_load_lds_dwordx4 v160, s[72:73]
	s_waitcnt vmcnt(6)
	s_barrier
	v_mfma_f32_16x16x32_bf16 v[56:59], v[206:209], v[144:147], v[56:59]
	v_mfma_f32_16x16x32_bf16 v[48:51], v[214:217], v[144:147], v[48:51]
	v_mfma_f32_16x16x32_bf16 v[40:43], v[206:209], v[152:155], v[40:43]
	v_mfma_f32_16x16x32_bf16 v[32:35], v[214:217], v[152:155], v[32:35]
	v_mfma_f32_16x16x32_bf16 v[24:27], v[206:209], v[170:173], v[24:27]
	v_mfma_f32_16x16x32_bf16 v[16:19], v[214:217], v[170:173], v[16:19]
	v_mfma_f32_16x16x32_bf16 v[8:11], v[206:209], v[192:195], v[8:11]
	v_mfma_f32_16x16x32_bf16 v[0:3], v[214:217], v[192:195], v[0:3]
	v_mfma_f32_16x16x32_bf16 v[56:59], v[210:213], v[148:151], v[56:59]
	v_mfma_f32_16x16x32_bf16 v[48:51], v[232:235], v[148:151], v[48:51]
	v_mfma_f32_16x16x32_bf16 v[40:43], v[210:213], v[166:169], v[40:43]
	v_mfma_f32_16x16x32_bf16 v[32:35], v[232:235], v[166:169], v[32:35]
	v_mfma_f32_16x16x32_bf16 v[24:27], v[210:213], v[188:191], v[24:27]
	v_mfma_f32_16x16x32_bf16 v[16:19], v[232:235], v[188:191], v[16:19]
	v_mfma_f32_16x16x32_bf16 v[8:11], v[210:213], v[202:205], v[8:11]
	v_mfma_f32_16x16x32_bf16 v[0:3], v[232:235], v[202:205], v[0:3]
	s_add_i32 s28, 0, 0x18000
	s_barrier
	ds_read_b128 v[128:131], v174 offset:32768
	ds_read_b128 v[132:135], v174 offset:33792
	ds_read_b128 v[136:139], v174 offset:34816
	ds_read_b128 v[140:143], v174 offset:35840
	s_add_u32 s98, s52, 0x40000
	s_addc_u32 s99, s53, 0
	s_mov_b32 m0, s58
	ds_read_b128 v[144:147], v201 offset:32768
	ds_read_b128 v[152:155], v201 offset:34816
	ds_read_b128 v[170:173], v201 offset:36864
	ds_read_b128 v[192:195], v201 offset:38912
	ds_read_b128 v[148:151], v201 offset:33792
	ds_read_b128 v[166:169], v201 offset:35840
	ds_read_b128 v[188:191], v201 offset:37888
	ds_read_b128 v[202:205], v201 offset:39936
	global_load_lds_dwordx4 v156, s[98:99]
	s_mov_b32 m0, s59
	s_nop 0
	global_load_lds_dwordx4 v158, s[98:99]
	s_waitcnt lgkmcnt(8)
	s_barrier
	s_waitcnt lgkmcnt(7)
	v_mfma_f32_16x16x32_bf16 v[124:127], v[128:131], v[144:147], v[124:127]
	v_mfma_f32_16x16x32_bf16 v[116:119], v[136:139], v[144:147], v[116:119]
	s_waitcnt lgkmcnt(6)
	v_mfma_f32_16x16x32_bf16 v[108:111], v[128:131], v[152:155], v[108:111]
	v_mfma_f32_16x16x32_bf16 v[100:103], v[136:139], v[152:155], v[100:103]
	s_waitcnt lgkmcnt(5)
	v_mfma_f32_16x16x32_bf16 v[92:95], v[128:131], v[170:173], v[92:95]
	v_mfma_f32_16x16x32_bf16 v[84:87], v[136:139], v[170:173], v[84:87]
	s_waitcnt lgkmcnt(4)
	v_mfma_f32_16x16x32_bf16 v[76:79], v[128:131], v[192:195], v[76:79]
	v_mfma_f32_16x16x32_bf16 v[68:71], v[136:139], v[192:195], v[68:71]
	s_waitcnt lgkmcnt(3)
	v_mfma_f32_16x16x32_bf16 v[124:127], v[132:135], v[148:151], v[124:127]
	v_mfma_f32_16x16x32_bf16 v[116:119], v[140:143], v[148:151], v[116:119]
	s_waitcnt lgkmcnt(2)
	v_mfma_f32_16x16x32_bf16 v[108:111], v[132:135], v[166:169], v[108:111]
	v_mfma_f32_16x16x32_bf16 v[100:103], v[140:143], v[166:169], v[100:103]
	s_waitcnt lgkmcnt(1)
	v_mfma_f32_16x16x32_bf16 v[92:95], v[132:135], v[188:191], v[92:95]
	v_mfma_f32_16x16x32_bf16 v[84:87], v[140:143], v[188:191], v[84:87]
	s_waitcnt lgkmcnt(0)
	v_mfma_f32_16x16x32_bf16 v[76:79], v[132:135], v[202:205], v[76:79]
	v_mfma_f32_16x16x32_bf16 v[68:71], v[140:143], v[202:205], v[68:71]
	s_barrier
	s_add_i32 s29, 0, 0x1c000
	s_add_i32 s28, s28, s55
	s_add_i32 m0, s28, 0xffffff80
	ds_read_b128 v[206:209], v174 offset:49152
	ds_read_b128 v[210:213], v174 offset:50176
	ds_read_b128 v[214:217], v174 offset:51200
	ds_read_b128 v[232:235], v174 offset:52224
	global_load_lds_dwordx4 v176, s[50:51] offset:128
	s_add_i32 m0, s28, 0x1f80
	s_nop 0
	global_load_lds_dwordx4 v160, s[50:51] offset:128
	s_barrier
	s_waitcnt lgkmcnt(3)
	v_mfma_f32_16x16x32_bf16 v[120:123], v[206:209], v[144:147], v[120:123]
	s_waitcnt lgkmcnt(1)
	v_mfma_f32_16x16x32_bf16 v[112:115], v[214:217], v[144:147], v[112:115]
	v_mfma_f32_16x16x32_bf16 v[104:107], v[206:209], v[152:155], v[104:107]
	v_mfma_f32_16x16x32_bf16 v[96:99], v[214:217], v[152:155], v[96:99]
	v_mfma_f32_16x16x32_bf16 v[88:91], v[206:209], v[170:173], v[88:91]
	v_mfma_f32_16x16x32_bf16 v[80:83], v[214:217], v[170:173], v[80:83]
	v_mfma_f32_16x16x32_bf16 v[72:75], v[206:209], v[192:195], v[72:75]
	v_mfma_f32_16x16x32_bf16 v[64:67], v[214:217], v[192:195], v[64:67]
	v_mfma_f32_16x16x32_bf16 v[120:123], v[210:213], v[148:151], v[120:123]
	s_waitcnt lgkmcnt(0)
	v_mfma_f32_16x16x32_bf16 v[112:115], v[232:235], v[148:151], v[112:115]
	v_mfma_f32_16x16x32_bf16 v[104:107], v[210:213], v[166:169], v[104:107]
	v_mfma_f32_16x16x32_bf16 v[96:99], v[232:235], v[166:169], v[96:99]
	v_mfma_f32_16x16x32_bf16 v[88:91], v[210:213], v[188:191], v[88:91]
	v_mfma_f32_16x16x32_bf16 v[80:83], v[232:235], v[188:191], v[80:83]
	v_mfma_f32_16x16x32_bf16 v[72:75], v[210:213], v[202:205], v[72:75]
	v_mfma_f32_16x16x32_bf16 v[64:67], v[232:235], v[202:205], v[64:67]
	s_add_i32 m0, s62, 0xffffff80
	s_barrier
	ds_read_b128 v[144:147], v201 offset:49152
	ds_read_b128 v[152:155], v201 offset:51200
	ds_read_b128 v[170:173], v201 offset:53248
	ds_read_b128 v[192:195], v201 offset:55296
	ds_read_b128 v[148:151], v201 offset:50176
	ds_read_b128 v[166:169], v201 offset:52224
	ds_read_b128 v[188:191], v201 offset:54272
	ds_read_b128 v[202:205], v201 offset:56320
	global_load_lds_dwordx4 v156, s[52:53] offset:128
	s_add_i32 m0, s63, 0xffffff80
	s_nop 0
	global_load_lds_dwordx4 v158, s[52:53] offset:128
	s_barrier
	s_waitcnt lgkmcnt(7)
	v_mfma_f32_16x16x32_bf16 v[60:63], v[128:131], v[144:147], v[60:63]
	v_mfma_f32_16x16x32_bf16 v[52:55], v[136:139], v[144:147], v[52:55]
	s_waitcnt lgkmcnt(6)
	v_mfma_f32_16x16x32_bf16 v[44:47], v[128:131], v[152:155], v[44:47]
	v_mfma_f32_16x16x32_bf16 v[36:39], v[136:139], v[152:155], v[36:39]
	s_waitcnt lgkmcnt(5)
	v_mfma_f32_16x16x32_bf16 v[28:31], v[128:131], v[170:173], v[28:31]
	v_mfma_f32_16x16x32_bf16 v[20:23], v[136:139], v[170:173], v[20:23]
	s_waitcnt lgkmcnt(4)
	v_mfma_f32_16x16x32_bf16 v[12:15], v[128:131], v[192:195], v[12:15]
	v_mfma_f32_16x16x32_bf16 v[4:7], v[136:139], v[192:195], v[4:7]
	s_waitcnt lgkmcnt(3)
	v_mfma_f32_16x16x32_bf16 v[60:63], v[132:135], v[148:151], v[60:63]
	v_mfma_f32_16x16x32_bf16 v[52:55], v[140:143], v[148:151], v[52:55]
	s_waitcnt lgkmcnt(2)
	v_mfma_f32_16x16x32_bf16 v[44:47], v[132:135], v[166:169], v[44:47]
	v_mfma_f32_16x16x32_bf16 v[36:39], v[140:143], v[166:169], v[36:39]
	s_waitcnt lgkmcnt(1)
	v_mfma_f32_16x16x32_bf16 v[28:31], v[132:135], v[188:191], v[28:31]
	v_mfma_f32_16x16x32_bf16 v[20:23], v[140:143], v[188:191], v[20:23]
	s_waitcnt lgkmcnt(0)
	v_mfma_f32_16x16x32_bf16 v[12:15], v[132:135], v[202:205], v[12:15]
	v_mfma_f32_16x16x32_bf16 v[4:7], v[140:143], v[202:205], v[4:7]
	s_barrier
	s_add_u32 s50, s50, 0x40080
	s_addc_u32 s51, s51, 0
	s_add_i32 s28, s29, s55
	s_mov_b32 m0, s28
	s_nop 0
	global_load_lds_dwordx4 v176, s[50:51]
	s_add_i32 m0, s28, 0x2000
	s_nop 0
	global_load_lds_dwordx4 v160, s[50:51]
	s_waitcnt vmcnt(6)
	s_barrier
	v_mfma_f32_16x16x32_bf16 v[56:59], v[206:209], v[144:147], v[56:59]
	v_mfma_f32_16x16x32_bf16 v[48:51], v[214:217], v[144:147], v[48:51]
	v_mfma_f32_16x16x32_bf16 v[40:43], v[206:209], v[152:155], v[40:43]
	v_mfma_f32_16x16x32_bf16 v[32:35], v[214:217], v[152:155], v[32:35]
	v_mfma_f32_16x16x32_bf16 v[24:27], v[206:209], v[170:173], v[24:27]
	v_mfma_f32_16x16x32_bf16 v[16:19], v[214:217], v[170:173], v[16:19]
	v_mfma_f32_16x16x32_bf16 v[8:11], v[206:209], v[192:195], v[8:11]
	v_mfma_f32_16x16x32_bf16 v[0:3], v[214:217], v[192:195], v[0:3]
	v_mfma_f32_16x16x32_bf16 v[56:59], v[210:213], v[148:151], v[56:59]
	v_mfma_f32_16x16x32_bf16 v[48:51], v[232:235], v[148:151], v[48:51]
	v_mfma_f32_16x16x32_bf16 v[40:43], v[210:213], v[166:169], v[40:43]
	v_mfma_f32_16x16x32_bf16 v[32:35], v[232:235], v[166:169], v[32:35]
	v_mfma_f32_16x16x32_bf16 v[24:27], v[210:213], v[188:191], v[24:27]
	v_mfma_f32_16x16x32_bf16 v[16:19], v[232:235], v[188:191], v[16:19]
	v_mfma_f32_16x16x32_bf16 v[8:11], v[210:213], v[202:205], v[8:11]
	v_mfma_f32_16x16x32_bf16 v[0:3], v[232:235], v[202:205], v[0:3]
	s_add_i32 s70, s70, 2
	s_add_u32 s6, s6, 0x100
	s_addc_u32 s7, s7, 0
	s_add_u32 s68, s68, 0x100
	s_addc_u32 s69, s69, 0
	s_cmp_lt_u32 s70, 14
	s_barrier
	s_cbranch_scc1 .LBB0_1436
	s_cmpk_gt_u32 s24, 0xff
	s_cbranch_scc1 .Ltb_e1_skip
	s_barrier
.Ltb_e1_skip:
	v_mov_b32_e32 v134, v199
	v_mov_b32_e32 v128, v198
	s_lshl_b32 s4, s4, 8
	s_add_i32 s4, s4, s60
	v_add_u32_e32 v192, s4, v128
	v_lshlrev_b32_e32 v128, 2, v134
	v_ashrrev_i32_e32 v129, 31, v128
	v_ashrrev_i32_e32 v193, 31, v192
	v_add_u32_e32 v190, 16, v192
	v_lshl_add_u64 v[132:133], v[128:129], 2, s[8:9]
	v_lshlrev_b64 v[128:129], 6, v[192:193]
	v_ashrrev_i32_e32 v191, 31, v190
	v_add_u32_e32 v188, 32, v192
	v_lshl_add_u64 v[128:129], v[132:133], 0, v[128:129]
	v_lshlrev_b64 v[130:131], 6, v[190:191]
	v_ashrrev_i32_e32 v189, 31, v188
	v_lshl_add_u64 v[130:131], v[132:133], 0, v[130:131]
	global_load_dwordx4 v[202:205], v[128:129], off
	global_load_dwordx4 v[144:147], v[130:131], off
	v_lshlrev_b64 v[128:129], 6, v[188:189]
	v_add_u32_e32 v174, 48, v192
	v_lshl_add_u64 v[128:129], v[132:133], 0, v[128:129]
	v_ashrrev_i32_e32 v175, 31, v174
	global_load_dwordx4 v[148:151], v[128:129], off
	v_lshlrev_b64 v[128:129], 6, v[174:175]
	v_lshl_add_u64 v[128:129], v[132:133], 0, v[128:129]
	global_load_dwordx4 v[152:155], v[128:129], off
	v_add_u32_e32 v172, 0x80, v192
	v_ashrrev_i32_e32 v173, 31, v172
	v_lshlrev_b64 v[128:129], 6, v[172:173]
	v_lshl_add_u64 v[128:129], v[132:133], 0, v[128:129]
	global_load_dwordx4 v[140:143], v[128:129], off
	v_add_u32_e32 v170, 0x90, v192
	v_ashrrev_i32_e32 v171, 31, v170
	v_lshlrev_b64 v[128:129], 6, v[170:171]
	v_lshl_add_u64 v[128:129], v[132:133], 0, v[128:129]
	global_load_dwordx4 v[128:131], v[128:129], off
	s_lshl_b32 s5, s5, 7
	v_add_u32_e32 v168, 0xa0, v192
	v_add_u32_e32 v166, 0xb0, v192
	s_or_b32 s5, s5, s61
	v_ashrrev_i32_e32 v169, 31, v168
	v_ashrrev_i32_e32 v167, 31, v166
	v_lshl_add_u32 v194, v134, 3, s5
	v_lshlrev_b64 v[134:135], 6, v[168:169]
	v_lshlrev_b64 v[136:137], 6, v[166:167]
	v_lshl_add_u64 v[134:135], v[132:133], 0, v[134:135]
	v_lshl_add_u64 v[132:133], v[132:133], 0, v[136:137]
	global_load_dwordx4 v[136:139], v[134:135], off
	s_nop 0
	global_load_dwordx4 v[132:135], v[132:133], off
	s_mov_b32 s4, 0x358637bd
	v_mov_b64_e32 v[196:197], s[4:5]
	v_ashrrev_i32_e32 v195, 31, v194
	s_mov_b64 s[50:51], s[20:21]
	s_waitcnt vmcnt(0)
	v_mov_b32_e32 v206, v203
	v_mov_b32_e32 v207, v204
	v_mov_b32_e32 v203, v205
	v_mov_b32_e32 v204, v145
	v_mov_b32_e32 v205, v146
	v_mov_b32_e32 v145, v147
	v_pk_add_f32 v[202:203], v[206:207], v[202:203]
	v_mov_b32_e32 v146, v149
	v_mov_b32_e32 v147, v150
	v_mov_b32_e32 v149, v151
	v_mov_b32_e32 v150, v153
	v_mov_b32_e32 v151, v154
	v_mov_b32_e32 v153, v155
	v_pk_add_f32 v[144:145], v[204:205], v[144:145]
	v_mov_b32_e32 v155, v202
	v_pk_add_f32 v[146:147], v[146:147], v[148:149]
	v_pk_add_f32 v[148:149], v[150:151], v[152:153]
	v_mov_b32_e32 v154, v144
	v_mov_b32_e32 v202, v145
	v_mov_b32_e32 v144, v148
	v_mov_b32_e32 v145, v146
	v_mov_b32_e32 v146, v149
	v_pk_add_f32 v[148:149], v[154:155], v[202:203]
	v_pk_add_f32 v[144:145], v[144:145], v[146:147]
	v_mov_b32_e32 v147, v149
	v_mov_b32_e32 v146, v148
	v_mov_b32_e32 v151, v145
	v_mov_b32_e32 v150, v144
	v_mov_b32_e32 v152, v141
	v_mov_b32_e32 v153, v142
	v_mov_b32_e32 v141, v143
	s_waitcnt lgkmcnt(0)
	v_permlane16_swap_b32 v149, v147
	v_permlane16_swap_b32 v148, v146
	v_pk_add_f32 v[142:143], v[148:149], v[146:147]
	v_mov_b32_e32 v147, v143
	v_mov_b32_e32 v146, v142
	v_permlane16_swap_b32 v145, v151
	v_permlane16_swap_b32 v144, v150
	v_pk_add_f32 v[144:145], v[144:145], v[150:151]
	v_mov_b32_e32 v149, v145
	v_mov_b32_e32 v148, v144
	v_mov_b32_e32 v150, v129
	s_waitcnt lgkmcnt(0)
	v_permlane32_swap_b32 v143, v147
	v_permlane32_swap_b32 v142, v146
	v_pk_add_f32 v[142:143], v[142:143], v[146:147]
	v_mov_b32_e32 v151, v130
	v_pk_fma_f32 v[142:143], v[142:143], s[30:31], v[196:197] op_sel_hi:[1,0,0]
	s_waitcnt lgkmcnt(0)
	v_permlane32_swap_b32 v145, v149
	v_permlane32_swap_b32 v144, v148
	v_pk_add_f32 v[144:145], v[144:145], v[148:149]
	v_mul_f32_e32 v129, 0x4b800000, v143
	v_cmp_gt_f32_e32 vcc, s86, v143
	v_pk_fma_f32 v[146:147], v[144:145], s[30:31], v[196:197] op_sel_hi:[1,0,0]
	v_mul_f32_e32 v130, 0x4b800000, v142
	v_cndmask_b32_e32 v129, v143, v129, vcc
	v_rsq_f32_e32 v129, v129
	v_cmp_gt_f32_e64 s[4:5], s86, v142
	v_mul_f32_e32 v144, 0x4b800000, v147
	v_cmp_gt_f32_e64 s[6:7], s86, v147
	v_cndmask_b32_e64 v130, v142, v130, s[4:5]
	v_rsq_f32_e32 v142, v130
	v_cndmask_b32_e64 v130, v147, v144, s[6:7]
	v_rsq_f32_e32 v143, v130
	v_mul_f32_e32 v130, 0x45800000, v129
	v_cndmask_b32_e32 v144, v129, v130, vcc
	v_mov_b32_e32 v129, v131
	v_pk_add_f32 v[140:141], v[152:153], v[140:141]
	v_pk_add_f32 v[128:129], v[150:151], v[128:129]
	v_mov_b32_e32 v131, v140
	v_mov_b32_e32 v130, v128
	v_mov_b32_e32 v140, v129
	v_pk_add_f32 v[128:129], v[130:131], v[140:141]
	v_mov_b32_e32 v131, v129
	v_mov_b32_e32 v130, v128
	v_mul_f32_e32 v145, 0x45800000, v142
	v_cndmask_b32_e64 v142, v142, v145, s[4:5]
	v_mul_f32_e32 v140, 0x4b800000, v146
	v_cmp_gt_f32_e32 vcc, s86, v146
	s_waitcnt lgkmcnt(0)
	v_permlane16_swap_b32 v129, v131
	v_permlane16_swap_b32 v128, v130
	v_pk_add_f32 v[128:129], v[128:129], v[130:131]
	v_mov_b32_e32 v131, v129
	v_mov_b32_e32 v130, v128
	v_cndmask_b32_e32 v140, v146, v140, vcc
	v_rsq_f32_e32 v141, v140
	v_mul_f32_e32 v140, 0x45800000, v143
	v_cndmask_b32_e64 v140, v143, v140, s[6:7]
	s_waitcnt lgkmcnt(0)
	v_permlane32_swap_b32 v129, v131
	v_permlane32_swap_b32 v128, v130
	v_pk_add_f32 v[128:129], v[128:129], v[130:131]
	v_mov_b32_e32 v131, v138
	v_pk_fma_f32 v[128:129], v[128:129], s[30:31], v[196:197] op_sel_hi:[1,0,0]
	v_mul_f32_e32 v143, 0x45800000, v141
	v_mul_f32_e32 v130, 0x4b800000, v129
	v_cmp_gt_f32_e64 s[4:5], s86, v129
	v_cmp_gt_f32_e64 s[6:7], s86, v128
	v_pk_mul_f32 v[110:111], v[110:111], v[142:143] op_sel_hi:[1,0]
	v_cndmask_b32_e64 v129, v129, v130, s[4:5]
	v_mov_b32_e32 v130, v137
	v_mov_b32_e32 v137, v139
	v_pk_add_f32 v[130:131], v[130:131], v[136:137]
	v_mov_b32_e32 v136, v133
	v_mov_b32_e32 v137, v134
	v_mov_b32_e32 v133, v135
	v_pk_add_f32 v[132:133], v[136:137], v[132:133]
	v_mov_b32_e32 v135, v130
	v_mov_b32_e32 v134, v132
	v_mov_b32_e32 v130, v133
	v_pk_add_f32 v[130:131], v[134:135], v[130:131]
	v_mov_b32_e32 v133, v131
	v_mov_b32_e32 v132, v130
	v_rsq_f32_e32 v145, v129
	v_mul_f32_e32 v129, 0x4b800000, v128
	v_cndmask_b32_e64 v128, v128, v129, s[6:7]
	v_rsq_f32_e32 v135, v128
	s_waitcnt lgkmcnt(0)
	v_permlane16_swap_b32 v131, v133
	v_permlane16_swap_b32 v130, v132
	v_pk_add_f32 v[128:129], v[130:131], v[132:133]
	v_mov_b32_e32 v131, v129
	v_mov_b32_e32 v130, v128
	v_pk_mul_f32 v[126:127], v[126:127], v[144:145] op_sel_hi:[1,0]
	v_pk_mul_f32 v[122:123], v[122:123], v[144:145] op_sel_hi:[1,0]
	v_pk_mul_f32 v[116:117], v[116:117], v[144:145] op_sel_hi:[1,0]
	v_pk_mul_f32 v[124:125], v[124:125], v[144:145] op_sel_hi:[1,0]
	v_pk_mul_f32 v[138:139], v[126:127], s[44:45] op_sel_hi:[1,0]
	v_pk_mul_f32 v[120:121], v[120:121], v[144:145] op_sel_hi:[1,0]
	v_pk_mul_f32 v[122:123], v[126:127], v[122:123]
	v_pk_mul_f32 v[118:119], v[118:119], v[144:145] op_sel_hi:[1,0]
	v_pk_mul_f32 v[126:127], v[116:117], s[44:45] op_sel_hi:[1,0]
	v_pk_mul_f32 v[146:147], v[124:125], s[44:45] op_sel_hi:[1,0]
	v_pk_mul_f32 v[120:121], v[124:125], v[120:121]
	v_pk_mul_f32 v[124:125], v[118:119], s[44:45] op_sel_hi:[1,0]
	v_exp_f32_e32 v126, v126
	v_exp_f32_e32 v127, v127
	s_waitcnt lgkmcnt(0)
	v_permlane32_swap_b32 v129, v131
	v_permlane32_swap_b32 v128, v130
	v_pk_add_f32 v[128:129], v[128:129], v[130:131]
	v_exp_f32_e32 v146, v146
	v_exp_f32_e32 v138, v138
	v_exp_f32_e32 v139, v139
	v_exp_f32_e32 v147, v147
	v_exp_f32_e32 v124, v124
	v_exp_f32_e32 v125, v125
	v_pk_fma_f32 v[128:129], v[128:129], s[30:31], v[196:197] op_sel_hi:[1,0,0]
	v_cndmask_b32_e32 v136, v141, v143, vcc
	v_mul_f32_e32 v132, 0x45800000, v145
	v_mul_f32_e32 v130, 0x4b800000, v129
	v_cmp_gt_f32_e32 vcc, s86, v129
	v_cndmask_b32_e64 v134, v145, v132, s[4:5]
	v_cmp_gt_f32_e64 s[4:5], s86, v128
	v_cndmask_b32_e32 v129, v129, v130, vcc
	v_mul_f32_e32 v130, 0x4b800000, v128
	v_pk_add_f32 v[126:127], v[126:127], 1.0 op_sel_hi:[1,0]
	v_rsq_f32_e32 v129, v129
	v_cndmask_b32_e64 v128, v128, v130, s[4:5]
	v_pk_add_f32 v[138:139], v[138:139], 1.0 op_sel_hi:[1,0]
	v_pk_add_f32 v[146:147], v[146:147], 1.0 op_sel_hi:[1,0]
	v_pk_add_f32 v[124:125], v[124:125], 1.0 op_sel_hi:[1,0]
	v_rcp_f32_e32 v126, v126
	v_rcp_f32_e32 v127, v127
	v_rsq_f32_e32 v128, v128
	v_rcp_f32_e32 v146, v146
	v_rcp_f32_e32 v138, v138
	v_rcp_f32_e32 v139, v139
	v_rcp_f32_e32 v147, v147
	v_rcp_f32_e32 v124, v124
	v_rcp_f32_e32 v125, v125
	v_pk_mul_f32 v[112:113], v[112:113], v[144:145] op_sel_hi:[1,0]
	v_pk_mul_f32 v[114:115], v[114:115], v[144:145] op_sel_hi:[1,0]
	v_pk_mul_f32 v[112:113], v[116:117], v[112:113]
	v_mul_f32_e32 v130, 0x45800000, v129
	v_pk_mul_f32 v[114:115], v[118:119], v[114:115]
	v_pk_mul_f32 v[112:113], v[112:113], v[126:127]
	v_mov_b64_e32 v[126:127], 0
	v_cndmask_b32_e32 v130, v129, v130, vcc
	v_mul_f32_e32 v129, 0x45800000, v128
	v_pk_mul_f32 v[122:123], v[122:123], v[138:139]
	v_pk_mul_f32 v[120:121], v[120:121], v[146:147]
	v_pk_mul_f32 v[114:115], v[114:115], v[124:125]
	v_mov_b64_e32 v[124:125], 0
	v_cvt_pk_bf16_f32 v116, v120, v121
	v_cvt_pk_bf16_f32 v117, v122, v123
	v_mov_b64_e32 v[122:123], 0
	v_cvt_pk_bf16_f32 v118, v112, v113
	v_mov_b64_e32 v[112:113], s[10:11]
	v_cndmask_b32_e64 v128, v128, v129, s[4:5]
	v_cvt_pk_bf16_f32 v119, v114, v115
	v_mad_i64_i32 v[120:121], s[4:5], v192, s35, v[112:113]
	v_lshlrev_b64 v[114:115], 1, v[194:195]
	v_lshl_add_u64 v[120:121], v[120:121], 0, v[114:115]
	v_pk_mul_f32 v[108:109], v[108:109], v[142:143] op_sel_hi:[1,0]
	v_pk_mul_f32 v[106:107], v[106:107], v[142:143] op_sel_hi:[1,0]
	v_pk_mul_f32 v[104:105], v[104:105], v[142:143] op_sel_hi:[1,0]
	v_pk_mul_f32 v[102:103], v[102:103], v[142:143] op_sel_hi:[1,0]
	v_pk_mul_f32 v[100:101], v[100:101], v[142:143] op_sel_hi:[1,0]
	global_store_dwordx4 v[120:121], v[116:119], off
	v_pk_mul_f32 v[104:105], v[108:109], v[104:105]
	v_pk_mul_f32 v[106:107], v[110:111], v[106:107]
	v_pk_mul_f32 v[116:117], v[110:111], s[44:45] op_sel_hi:[1,0]
	v_mov_b64_e32 v[120:121], 0
	v_pk_mul_f32 v[118:119], v[108:109], s[44:45] op_sel_hi:[1,0]
	v_pk_mul_f32 v[108:109], v[102:103], s[44:45] op_sel_hi:[1,0]
	v_pk_mul_f32 v[110:111], v[100:101], s[44:45] op_sel_hi:[1,0]
	v_exp_f32_e32 v108, v108
	v_exp_f32_e32 v110, v110
	v_exp_f32_e32 v109, v109
	v_exp_f32_e32 v111, v111
	v_exp_f32_e32 v118, v118
	v_exp_f32_e32 v116, v116
	v_exp_f32_e32 v117, v117
	v_exp_f32_e32 v119, v119
	v_pk_add_f32 v[108:109], v[108:109], 1.0 op_sel_hi:[1,0]
	v_pk_add_f32 v[110:111], v[110:111], 1.0 op_sel_hi:[1,0]
	v_pk_add_f32 v[116:117], v[116:117], 1.0 op_sel_hi:[1,0]
	v_pk_add_f32 v[118:119], v[118:119], 1.0 op_sel_hi:[1,0]
	v_rcp_f32_e32 v110, v110
	v_rcp_f32_e32 v108, v108
	v_rcp_f32_e32 v109, v109
	v_rcp_f32_e32 v111, v111
	v_rcp_f32_e32 v118, v118
	v_rcp_f32_e32 v116, v116
	v_rcp_f32_e32 v117, v117
	v_rcp_f32_e32 v119, v119
	v_pk_mul_f32 v[98:99], v[98:99], v[142:143] op_sel_hi:[1,0]
	v_pk_mul_f32 v[96:97], v[96:97], v[142:143] op_sel_hi:[1,0]
	v_pk_mul_f32 v[98:99], v[102:103], v[98:99]
	v_mov_b64_e32 v[102:103], 0
	v_pk_mul_f32 v[96:97], v[100:101], v[96:97]
	v_pk_mul_f32 v[100:101], v[98:99], v[108:109]
	v_mov_b64_e32 v[108:109], 0
	v_pk_mul_f32 v[98:99], v[96:97], v[110:111]
	v_mov_b64_e32 v[110:111], 0
	v_pk_mul_f32 v[106:107], v[106:107], v[116:117]
	v_mov_b64_e32 v[116:117], 0
	v_pk_mul_f32 v[104:105], v[104:105], v[118:119]
	v_mov_b64_e32 v[118:119], 0
	v_pk_mul_f32 v[94:95], v[94:95], v[140:141] op_sel_hi:[1,0]
	v_cvt_pk_bf16_f32 v96, v104, v105
	v_mov_b64_e32 v[104:105], 0
	v_cvt_pk_bf16_f32 v97, v106, v107
	v_mov_b64_e32 v[106:107], 0
	v_cvt_pk_bf16_f32 v98, v98, v99
	v_cvt_pk_bf16_f32 v99, v100, v101
	v_mad_i64_i32 v[100:101], s[4:5], v190, s35, v[112:113]
	v_lshl_add_u64 v[100:101], v[100:101], 0, v[114:115]
	v_pk_mul_f32 v[92:93], v[92:93], v[140:141] op_sel_hi:[1,0]
	v_pk_mul_f32 v[90:91], v[90:91], v[140:141] op_sel_hi:[1,0]
	v_pk_mul_f32 v[88:89], v[88:89], v[140:141] op_sel_hi:[1,0]
	v_pk_mul_f32 v[86:87], v[86:87], v[140:141] op_sel_hi:[1,0]
	v_pk_mul_f32 v[84:85], v[84:85], v[140:141] op_sel_hi:[1,0]
	global_store_dwordx4 v[100:101], v[96:99], off
	v_pk_mul_f32 v[88:89], v[92:93], v[88:89]
	v_pk_mul_f32 v[90:91], v[94:95], v[90:91]
	v_pk_mul_f32 v[96:97], v[94:95], s[44:45] op_sel_hi:[1,0]
	v_mov_b64_e32 v[100:101], 0
	v_pk_mul_f32 v[98:99], v[92:93], s[44:45] op_sel_hi:[1,0]
	v_pk_mul_f32 v[92:93], v[86:87], s[44:45] op_sel_hi:[1,0]
	v_pk_mul_f32 v[94:95], v[84:85], s[44:45] op_sel_hi:[1,0]
	v_exp_f32_e32 v92, v92
	v_exp_f32_e32 v94, v94
	v_exp_f32_e32 v93, v93
	v_exp_f32_e32 v95, v95
	v_exp_f32_e32 v98, v98
	v_exp_f32_e32 v96, v96
	v_exp_f32_e32 v97, v97
	v_exp_f32_e32 v99, v99
	v_pk_add_f32 v[92:93], v[92:93], 1.0 op_sel_hi:[1,0]
	v_pk_add_f32 v[94:95], v[94:95], 1.0 op_sel_hi:[1,0]
	v_pk_add_f32 v[96:97], v[96:97], 1.0 op_sel_hi:[1,0]
	v_pk_add_f32 v[98:99], v[98:99], 1.0 op_sel_hi:[1,0]
	v_rcp_f32_e32 v94, v94
	v_rcp_f32_e32 v92, v92
	v_rcp_f32_e32 v93, v93
	v_rcp_f32_e32 v95, v95
	v_rcp_f32_e32 v98, v98
	v_rcp_f32_e32 v96, v96
	v_rcp_f32_e32 v97, v97
	v_rcp_f32_e32 v99, v99
	v_pk_mul_f32 v[82:83], v[82:83], v[140:141] op_sel_hi:[1,0]
	v_pk_mul_f32 v[80:81], v[80:81], v[140:141] op_sel_hi:[1,0]
	v_pk_mul_f32 v[82:83], v[86:87], v[82:83]
	v_mov_b64_e32 v[86:87], 0
	v_pk_mul_f32 v[80:81], v[84:85], v[80:81]
	v_pk_mul_f32 v[84:85], v[82:83], v[92:93]
	v_mov_b64_e32 v[92:93], 0
	v_pk_mul_f32 v[82:83], v[80:81], v[94:95]
	v_mov_b64_e32 v[94:95], 0
	v_pk_mul_f32 v[90:91], v[90:91], v[96:97]
	v_mov_b64_e32 v[96:97], 0
	v_pk_mul_f32 v[88:89], v[88:89], v[98:99]
	v_mov_b64_e32 v[98:99], 0
	v_pk_mul_f32 v[78:79], v[78:79], v[136:137] op_sel_hi:[1,0]
	v_cvt_pk_bf16_f32 v80, v88, v89
	v_mov_b64_e32 v[88:89], 0
	v_cvt_pk_bf16_f32 v81, v90, v91
	v_mov_b64_e32 v[90:91], 0
	v_cvt_pk_bf16_f32 v82, v82, v83
	v_cvt_pk_bf16_f32 v83, v84, v85
	v_mad_i64_i32 v[84:85], s[4:5], v188, s35, v[112:113]
	v_lshl_add_u64 v[84:85], v[84:85], 0, v[114:115]
	v_pk_mul_f32 v[76:77], v[76:77], v[136:137] op_sel_hi:[1,0]
	v_pk_mul_f32 v[74:75], v[74:75], v[136:137] op_sel_hi:[1,0]
	v_pk_mul_f32 v[72:73], v[72:73], v[136:137] op_sel_hi:[1,0]
	v_pk_mul_f32 v[70:71], v[70:71], v[136:137] op_sel_hi:[1,0]
	v_pk_mul_f32 v[68:69], v[68:69], v[136:137] op_sel_hi:[1,0]
	global_store_dwordx4 v[84:85], v[80:83], off
	v_pk_mul_f32 v[72:73], v[76:77], v[72:73]
	v_pk_mul_f32 v[74:75], v[78:79], v[74:75]
	v_pk_mul_f32 v[80:81], v[78:79], s[44:45] op_sel_hi:[1,0]
	v_mov_b64_e32 v[84:85], 0
	v_pk_mul_f32 v[82:83], v[76:77], s[44:45] op_sel_hi:[1,0]
	v_pk_mul_f32 v[76:77], v[70:71], s[44:45] op_sel_hi:[1,0]
	v_pk_mul_f32 v[78:79], v[68:69], s[44:45] op_sel_hi:[1,0]
	v_exp_f32_e32 v76, v76
	v_exp_f32_e32 v78, v78
	v_exp_f32_e32 v77, v77
	v_exp_f32_e32 v79, v79
	v_exp_f32_e32 v82, v82
	v_exp_f32_e32 v80, v80
	v_exp_f32_e32 v81, v81
	v_exp_f32_e32 v83, v83
	v_pk_add_f32 v[76:77], v[76:77], 1.0 op_sel_hi:[1,0]
	v_pk_add_f32 v[78:79], v[78:79], 1.0 op_sel_hi:[1,0]
	v_pk_add_f32 v[80:81], v[80:81], 1.0 op_sel_hi:[1,0]
	v_pk_add_f32 v[82:83], v[82:83], 1.0 op_sel_hi:[1,0]
	v_rcp_f32_e32 v78, v78
	v_rcp_f32_e32 v76, v76
	v_rcp_f32_e32 v77, v77
	v_rcp_f32_e32 v79, v79
	v_rcp_f32_e32 v82, v82
	v_rcp_f32_e32 v80, v80
	v_rcp_f32_e32 v81, v81
	v_rcp_f32_e32 v83, v83
	v_pk_mul_f32 v[66:67], v[66:67], v[136:137] op_sel_hi:[1,0]
	v_pk_mul_f32 v[64:65], v[64:65], v[136:137] op_sel_hi:[1,0]
	v_pk_mul_f32 v[66:67], v[70:71], v[66:67]
	v_mov_b64_e32 v[70:71], 0
	v_pk_mul_f32 v[64:65], v[68:69], v[64:65]
	v_pk_mul_f32 v[68:69], v[66:67], v[76:77]
	v_mov_b64_e32 v[76:77], 0
	v_pk_mul_f32 v[66:67], v[64:65], v[78:79]
	v_mov_b64_e32 v[78:79], 0
	v_pk_mul_f32 v[74:75], v[74:75], v[80:81]
	v_mov_b64_e32 v[80:81], 0
	v_pk_mul_f32 v[72:73], v[72:73], v[82:83]
	v_mov_b64_e32 v[82:83], 0
	v_pk_mul_f32 v[62:63], v[62:63], v[134:135] op_sel_hi:[1,0]
	v_cvt_pk_bf16_f32 v64, v72, v73
	v_mov_b64_e32 v[72:73], 0
	v_cvt_pk_bf16_f32 v65, v74, v75
	v_mov_b64_e32 v[74:75], 0
	v_cvt_pk_bf16_f32 v66, v66, v67
	v_cvt_pk_bf16_f32 v67, v68, v69
	v_mad_i64_i32 v[68:69], s[4:5], v174, s35, v[112:113]
	v_lshl_add_u64 v[68:69], v[68:69], 0, v[114:115]
	v_pk_mul_f32 v[60:61], v[60:61], v[134:135] op_sel_hi:[1,0]
	v_pk_mul_f32 v[58:59], v[58:59], v[134:135] op_sel_hi:[1,0]
	v_pk_mul_f32 v[56:57], v[56:57], v[134:135] op_sel_hi:[1,0]
	v_pk_mul_f32 v[54:55], v[54:55], v[134:135] op_sel_hi:[1,0]
	v_pk_mul_f32 v[52:53], v[52:53], v[134:135] op_sel_hi:[1,0]
	global_store_dwordx4 v[68:69], v[64:67], off
	v_pk_mul_f32 v[56:57], v[60:61], v[56:57]
	v_pk_mul_f32 v[58:59], v[62:63], v[58:59]
	v_pk_mul_f32 v[64:65], v[62:63], s[44:45] op_sel_hi:[1,0]
	v_mov_b64_e32 v[68:69], 0
	v_pk_mul_f32 v[66:67], v[60:61], s[44:45] op_sel_hi:[1,0]
	v_pk_mul_f32 v[60:61], v[54:55], s[44:45] op_sel_hi:[1,0]
	v_pk_mul_f32 v[62:63], v[52:53], s[44:45] op_sel_hi:[1,0]
	v_exp_f32_e32 v60, v60
	v_exp_f32_e32 v62, v62
	v_exp_f32_e32 v61, v61
	v_exp_f32_e32 v63, v63
	v_exp_f32_e32 v66, v66
	v_exp_f32_e32 v64, v64
	v_exp_f32_e32 v65, v65
	v_exp_f32_e32 v67, v67
	v_pk_add_f32 v[60:61], v[60:61], 1.0 op_sel_hi:[1,0]
	v_pk_add_f32 v[62:63], v[62:63], 1.0 op_sel_hi:[1,0]
	v_pk_add_f32 v[64:65], v[64:65], 1.0 op_sel_hi:[1,0]
	v_pk_add_f32 v[66:67], v[66:67], 1.0 op_sel_hi:[1,0]
	v_rcp_f32_e32 v62, v62
	v_rcp_f32_e32 v60, v60
	v_rcp_f32_e32 v61, v61
	v_rcp_f32_e32 v63, v63
	v_rcp_f32_e32 v66, v66
	v_rcp_f32_e32 v64, v64
	v_rcp_f32_e32 v65, v65
	v_rcp_f32_e32 v67, v67
	v_pk_mul_f32 v[50:51], v[50:51], v[134:135] op_sel_hi:[1,0]
	v_pk_mul_f32 v[48:49], v[48:49], v[134:135] op_sel_hi:[1,0]
	v_pk_mul_f32 v[50:51], v[54:55], v[50:51]
	v_mov_b64_e32 v[54:55], 0
	v_pk_mul_f32 v[48:49], v[52:53], v[48:49]
	v_mul_f32_e32 v132, 0x45800000, v135
	v_pk_mul_f32 v[52:53], v[50:51], v[60:61]
	v_mov_b64_e32 v[60:61], 0
	v_pk_mul_f32 v[50:51], v[48:49], v[62:63]
	v_mov_b64_e32 v[62:63], 0
	v_cndmask_b32_e64 v132, v135, v132, s[6:7]
	v_pk_mul_f32 v[58:59], v[58:59], v[64:65]
	v_mov_b64_e32 v[64:65], 0
	v_pk_mul_f32 v[56:57], v[56:57], v[66:67]
	v_mov_b64_e32 v[66:67], 0
	v_pk_mul_f32 v[46:47], v[46:47], v[132:133] op_sel_hi:[1,0]
	v_cvt_pk_bf16_f32 v48, v56, v57
	v_mov_b64_e32 v[56:57], 0
	v_cvt_pk_bf16_f32 v49, v58, v59
	v_mov_b64_e32 v[58:59], 0
	v_cvt_pk_bf16_f32 v50, v50, v51
	v_cvt_pk_bf16_f32 v51, v52, v53
	v_mad_i64_i32 v[52:53], s[4:5], v172, s35, v[112:113]
	v_lshl_add_u64 v[52:53], v[52:53], 0, v[114:115]
	v_pk_mul_f32 v[44:45], v[44:45], v[132:133] op_sel_hi:[1,0]
	v_pk_mul_f32 v[42:43], v[42:43], v[132:133] op_sel_hi:[1,0]
	v_pk_mul_f32 v[40:41], v[40:41], v[132:133] op_sel_hi:[1,0]
	v_pk_mul_f32 v[38:39], v[38:39], v[132:133] op_sel_hi:[1,0]
	v_pk_mul_f32 v[36:37], v[36:37], v[132:133] op_sel_hi:[1,0]
	global_store_dwordx4 v[52:53], v[48:51], off
	v_pk_mul_f32 v[40:41], v[44:45], v[40:41]
	v_pk_mul_f32 v[42:43], v[46:47], v[42:43]
	v_pk_mul_f32 v[48:49], v[46:47], s[44:45] op_sel_hi:[1,0]
	v_mov_b64_e32 v[52:53], 0
	v_pk_mul_f32 v[50:51], v[44:45], s[44:45] op_sel_hi:[1,0]
	v_pk_mul_f32 v[44:45], v[38:39], s[44:45] op_sel_hi:[1,0]
	v_pk_mul_f32 v[46:47], v[36:37], s[44:45] op_sel_hi:[1,0]
	v_exp_f32_e32 v44, v44
	v_exp_f32_e32 v46, v46
	v_exp_f32_e32 v45, v45
	v_exp_f32_e32 v47, v47
	v_exp_f32_e32 v50, v50
	v_exp_f32_e32 v48, v48
	v_exp_f32_e32 v49, v49
	v_exp_f32_e32 v51, v51
	v_pk_add_f32 v[44:45], v[44:45], 1.0 op_sel_hi:[1,0]
	v_pk_add_f32 v[46:47], v[46:47], 1.0 op_sel_hi:[1,0]
	v_pk_add_f32 v[48:49], v[48:49], 1.0 op_sel_hi:[1,0]
	v_pk_add_f32 v[50:51], v[50:51], 1.0 op_sel_hi:[1,0]
	v_rcp_f32_e32 v46, v46
	v_rcp_f32_e32 v44, v44
	v_rcp_f32_e32 v45, v45
	v_rcp_f32_e32 v47, v47
	v_rcp_f32_e32 v50, v50
	v_rcp_f32_e32 v48, v48
	v_rcp_f32_e32 v49, v49
	v_rcp_f32_e32 v51, v51
	v_pk_mul_f32 v[34:35], v[34:35], v[132:133] op_sel_hi:[1,0]
	v_pk_mul_f32 v[32:33], v[32:33], v[132:133] op_sel_hi:[1,0]
	v_pk_mul_f32 v[34:35], v[38:39], v[34:35]
	v_mov_b64_e32 v[38:39], 0
	v_pk_mul_f32 v[32:33], v[36:37], v[32:33]
	v_pk_mul_f32 v[36:37], v[34:35], v[44:45]
	v_mov_b64_e32 v[44:45], 0
	v_pk_mul_f32 v[34:35], v[32:33], v[46:47]
	v_mov_b64_e32 v[46:47], 0
	v_pk_mul_f32 v[42:43], v[42:43], v[48:49]
	v_mov_b64_e32 v[48:49], 0
	v_pk_mul_f32 v[40:41], v[40:41], v[50:51]
	v_mov_b64_e32 v[50:51], 0
	v_pk_mul_f32 v[30:31], v[30:31], v[130:131] op_sel_hi:[1,0]
	v_cvt_pk_bf16_f32 v32, v40, v41
	v_mov_b64_e32 v[40:41], 0
	v_cvt_pk_bf16_f32 v33, v42, v43
	v_mov_b64_e32 v[42:43], 0
	v_cvt_pk_bf16_f32 v34, v34, v35
	v_cvt_pk_bf16_f32 v35, v36, v37
	v_mad_i64_i32 v[36:37], s[4:5], v170, s35, v[112:113]
	v_lshl_add_u64 v[36:37], v[36:37], 0, v[114:115]
	v_pk_mul_f32 v[28:29], v[28:29], v[130:131] op_sel_hi:[1,0]
	v_pk_mul_f32 v[26:27], v[26:27], v[130:131] op_sel_hi:[1,0]
	v_pk_mul_f32 v[24:25], v[24:25], v[130:131] op_sel_hi:[1,0]
	v_pk_mul_f32 v[22:23], v[22:23], v[130:131] op_sel_hi:[1,0]
	v_pk_mul_f32 v[20:21], v[20:21], v[130:131] op_sel_hi:[1,0]
	global_store_dwordx4 v[36:37], v[32:35], off
	v_pk_mul_f32 v[24:25], v[28:29], v[24:25]
	v_pk_mul_f32 v[26:27], v[30:31], v[26:27]
	v_pk_mul_f32 v[32:33], v[30:31], s[44:45] op_sel_hi:[1,0]
	v_mov_b64_e32 v[36:37], 0
	v_pk_mul_f32 v[34:35], v[28:29], s[44:45] op_sel_hi:[1,0]
	v_pk_mul_f32 v[28:29], v[22:23], s[44:45] op_sel_hi:[1,0]
	v_pk_mul_f32 v[30:31], v[20:21], s[44:45] op_sel_hi:[1,0]
	v_exp_f32_e32 v28, v28
	v_exp_f32_e32 v30, v30
	v_exp_f32_e32 v29, v29
	v_exp_f32_e32 v31, v31
	v_exp_f32_e32 v34, v34
	v_exp_f32_e32 v32, v32
	v_exp_f32_e32 v33, v33
	v_exp_f32_e32 v35, v35
	v_pk_add_f32 v[28:29], v[28:29], 1.0 op_sel_hi:[1,0]
	v_pk_add_f32 v[30:31], v[30:31], 1.0 op_sel_hi:[1,0]
	v_pk_add_f32 v[32:33], v[32:33], 1.0 op_sel_hi:[1,0]
	v_pk_add_f32 v[34:35], v[34:35], 1.0 op_sel_hi:[1,0]
	v_rcp_f32_e32 v30, v30
	v_rcp_f32_e32 v28, v28
	v_rcp_f32_e32 v29, v29
	v_rcp_f32_e32 v31, v31
	v_rcp_f32_e32 v34, v34
	v_rcp_f32_e32 v32, v32
	v_rcp_f32_e32 v33, v33
	v_rcp_f32_e32 v35, v35
	v_pk_mul_f32 v[18:19], v[18:19], v[130:131] op_sel_hi:[1,0]
	v_pk_mul_f32 v[16:17], v[16:17], v[130:131] op_sel_hi:[1,0]
	v_pk_mul_f32 v[18:19], v[22:23], v[18:19]
	v_mov_b64_e32 v[22:23], 0
	v_pk_mul_f32 v[16:17], v[20:21], v[16:17]
	v_pk_mul_f32 v[20:21], v[18:19], v[28:29]
	v_mov_b64_e32 v[28:29], 0
	v_pk_mul_f32 v[18:19], v[16:17], v[30:31]
	v_mov_b64_e32 v[30:31], 0
	v_pk_mul_f32 v[26:27], v[26:27], v[32:33]
	v_mov_b64_e32 v[32:33], 0
	v_pk_mul_f32 v[24:25], v[24:25], v[34:35]
	v_mov_b64_e32 v[34:35], 0
	v_pk_mul_f32 v[14:15], v[14:15], v[128:129] op_sel_hi:[1,0]
	v_cvt_pk_bf16_f32 v16, v24, v25
	v_mov_b64_e32 v[24:25], 0
	v_cvt_pk_bf16_f32 v17, v26, v27
	v_mov_b64_e32 v[26:27], 0
	v_cvt_pk_bf16_f32 v18, v18, v19
	v_cvt_pk_bf16_f32 v19, v20, v21
	v_mad_i64_i32 v[20:21], s[4:5], v168, s35, v[112:113]
	v_lshl_add_u64 v[20:21], v[20:21], 0, v[114:115]
	v_pk_mul_f32 v[12:13], v[12:13], v[128:129] op_sel_hi:[1,0]
	v_pk_mul_f32 v[10:11], v[10:11], v[128:129] op_sel_hi:[1,0]
	v_pk_mul_f32 v[8:9], v[8:9], v[128:129] op_sel_hi:[1,0]
	v_pk_mul_f32 v[6:7], v[6:7], v[128:129] op_sel_hi:[1,0]
	v_pk_mul_f32 v[4:5], v[4:5], v[128:129] op_sel_hi:[1,0]
	global_store_dwordx4 v[20:21], v[16:19], off
	v_pk_mul_f32 v[8:9], v[12:13], v[8:9]
	v_pk_mul_f32 v[10:11], v[14:15], v[10:11]
	v_pk_mul_f32 v[16:17], v[14:15], s[44:45] op_sel_hi:[1,0]
	v_mov_b64_e32 v[20:21], 0
	v_pk_mul_f32 v[18:19], v[12:13], s[44:45] op_sel_hi:[1,0]
	v_pk_mul_f32 v[12:13], v[6:7], s[44:45] op_sel_hi:[1,0]
	v_pk_mul_f32 v[14:15], v[4:5], s[44:45] op_sel_hi:[1,0]
	v_exp_f32_e32 v12, v12
	v_exp_f32_e32 v14, v14
	v_exp_f32_e32 v13, v13
	v_exp_f32_e32 v15, v15
	v_exp_f32_e32 v18, v18
	v_exp_f32_e32 v16, v16
	v_exp_f32_e32 v17, v17
	v_exp_f32_e32 v19, v19
	v_pk_add_f32 v[12:13], v[12:13], 1.0 op_sel_hi:[1,0]
	v_pk_add_f32 v[14:15], v[14:15], 1.0 op_sel_hi:[1,0]
	v_pk_add_f32 v[16:17], v[16:17], 1.0 op_sel_hi:[1,0]
	v_pk_add_f32 v[18:19], v[18:19], 1.0 op_sel_hi:[1,0]
	v_rcp_f32_e32 v14, v14
	v_rcp_f32_e32 v12, v12
	v_rcp_f32_e32 v13, v13
	v_rcp_f32_e32 v15, v15
	v_rcp_f32_e32 v18, v18
	v_rcp_f32_e32 v16, v16
	v_rcp_f32_e32 v17, v17
	v_rcp_f32_e32 v19, v19
	v_pk_mul_f32 v[2:3], v[2:3], v[128:129] op_sel_hi:[1,0]
	v_pk_mul_f32 v[0:1], v[0:1], v[128:129] op_sel_hi:[1,0]
	v_pk_mul_f32 v[2:3], v[6:7], v[2:3]
	v_mov_b64_e32 v[6:7], 0
	v_pk_mul_f32 v[0:1], v[4:5], v[0:1]
	v_pk_mul_f32 v[4:5], v[2:3], v[12:13]
	v_mov_b64_e32 v[12:13], 0
	v_pk_mul_f32 v[2:3], v[0:1], v[14:15]
	v_mov_b64_e32 v[14:15], 0
	v_pk_mul_f32 v[10:11], v[10:11], v[16:17]
	v_mov_b64_e32 v[16:17], 0
	v_pk_mul_f32 v[8:9], v[8:9], v[18:19]
	v_mov_b64_e32 v[18:19], 0
	s_andn2_b64 vcc, exec, s[2:3]
	v_cvt_pk_bf16_f32 v0, v8, v9
	v_mov_b64_e32 v[8:9], 0
	v_cvt_pk_bf16_f32 v1, v10, v11
	v_mov_b64_e32 v[10:11], 0
	v_cvt_pk_bf16_f32 v2, v2, v3
	v_cvt_pk_bf16_f32 v3, v4, v5
	v_mad_i64_i32 v[4:5], s[4:5], v166, s35, v[112:113]
	v_mov_b64_e32 v[112:113], 0
	v_lshl_add_u64 v[4:5], v[4:5], 0, v[114:115]
	v_mov_b64_e32 v[114:115], 0
	s_mov_b32 s4, s16
	s_mov_b32 s5, s12
	s_mov_b64 s[6:7], s[18:19]
	global_store_dwordx4 v[4:5], v[0:3], off
	s_cbranch_vccnz .LBB0_1429
	s_waitcnt vmcnt(0)
	s_cmpk_gt_u32 s24, 0xff
	s_cbranch_scc1 .LBB0_1440
